# WKV scan: y partials of two consecutive steps written with one ds_write2st64_b32
# speedup vs baseline: 1.0117x; 1.0021x over previous
.LBB0_545:
	s_mul_i32 s4, s93, 0x6000
	s_lshl_b32 s5, s93, 14
	v_add_u32_e32 v2, s4, v194
	v_add_u32_e32 v3, s4, v195
	v_add_u32_e32 v0, s5, v196
	ds_read_b128 v[24:27], v2 offset:16384
	ds_read_b64 v[44:45], v3 offset:12288
	ds_read_b128 v[36:39], v2 offset:8192
	ds_read_b128 v[28:31], v2 offset:4096
	ds_read_b128 v[32:35], v2 offset:20480
	ds_read_b128 v[40:43], v2 offset:0
	ds_read_b128 v[144:147], v2 offset:16640
	ds_read_b64 v[164:165], v3 offset:12544
	ds_read_b128 v[156:159], v2 offset:8448
	ds_read_b128 v[148:151], v2 offset:4352
	ds_read_b128 v[152:155], v2 offset:20736
	s_waitcnt lgkmcnt(5)
	v_pk_mul_f32 v[46:47], v[16:17], v[24:25] op_sel_hi:[1,0]
	v_pk_fma_f32 v[46:47], v[18:19], v[24:25], v[46:47] op_sel:[0,1,0] op_sel_hi:[1,1,1]
	v_pk_fma_f32 v[46:47], v[20:21], v[26:27], v[46:47] op_sel_hi:[1,0,1]
	v_pk_fma_f32 v[46:47], v[22:23], v[26:27], v[46:47] op_sel:[0,1,0] op_sel_hi:[1,1,1]
	ds_read_b128 v[160:163], v2 offset:256
	v_pk_mul_f32 v[168:169], v[44:45], v[36:37] op_sel_hi:[1,0]
	v_add_f32_dpp v48, v47, v46 quad_perm:[1,0,3,2] row_mask:0xf bank_mask:0xf bound_ctrl:1
	v_pk_mul_f32 v[170:171], v[44:45], v[36:37] op_sel:[0,1] op_sel_hi:[1,1]
	s_nop 0
	v_add_f32_dpp v48, v48, v48 quad_perm:[2,3,0,1] row_mask:0xf bank_mask:0xf bound_ctrl:1
	v_pk_mul_f32 v[172:173], v[44:45], v[38:39] op_sel_hi:[1,0]
	v_pk_mul_f32 v[174:175], v[44:45], v[38:39] op_sel:[0,1] op_sel_hi:[1,1]
	v_add_f32_dpp v48, v48, v48 row_ror:4 row_mask:0xf bank_mask:0xf bound_ctrl:1
	v_pk_fma_f32 v[168:169], v[16:17], v[28:29], v[168:169] op_sel_hi:[1,0,1]
	v_pk_fma_f32 v[170:171], v[18:19], v[28:29], v[170:171] op_sel:[0,1,0] op_sel_hi:[1,1,1]
	v_add_f32_dpp v48, v48, v48 row_ror:8 row_mask:0xf bank_mask:0xf bound_ctrl:1
	v_pk_fma_f32 v[172:173], v[20:21], v[30:31], v[172:173] op_sel_hi:[1,0,1]
	v_pk_fma_f32 v[174:175], v[22:23], v[30:31], v[174:175] op_sel:[0,1,0] op_sel_hi:[1,1,1]
	v_mov_b32_dpp v49, v48 quad_perm:[1,0,3,2] row_mask:0xf bank_mask:0xf bound_ctrl:1
	v_pk_fma_f32 v[16:17], v[48:49], v[32:33], v[168:169] op_sel_hi:[1,0,1] neg_lo:[0,1,0] neg_hi:[0,1,0]
	v_pk_fma_f32 v[18:19], v[48:49], v[32:33], v[170:171] op_sel:[0,1,0] op_sel_hi:[1,1,1] neg_lo:[0,1,0] neg_hi:[0,1,0]
	v_pk_fma_f32 v[20:21], v[48:49], v[34:35], v[172:173] op_sel_hi:[1,0,1] neg_lo:[0,1,0] neg_hi:[0,1,0]
	v_pk_fma_f32 v[22:23], v[48:49], v[34:35], v[174:175] op_sel:[0,1,0] op_sel_hi:[1,1,1] neg_lo:[0,1,0] neg_hi:[0,1,0]
	ds_read_b128 v[24:27], v2 offset:16896
	ds_read_b64 v[44:45], v3 offset:12800
	ds_read_b128 v[36:39], v2 offset:8704
	ds_read_b128 v[28:31], v2 offset:4608
	ds_read_b128 v[32:35], v2 offset:20992
	s_waitcnt lgkmcnt(5)
	v_pk_mul_f32 v[46:47], v[16:17], v[144:145] op_sel_hi:[1,0]
	v_pk_mul_f32 v[50:51], v[16:17], v[40:41] op_sel_hi:[1,0]
	v_pk_fma_f32 v[46:47], v[18:19], v[144:145], v[46:47] op_sel:[0,1,0] op_sel_hi:[1,1,1]
	v_pk_fma_f32 v[50:51], v[18:19], v[40:41], v[50:51] op_sel:[0,1,0] op_sel_hi:[1,1,1]
	v_pk_fma_f32 v[46:47], v[20:21], v[146:147], v[46:47] op_sel_hi:[1,0,1]
	v_pk_fma_f32 v[50:51], v[20:21], v[42:43], v[50:51] op_sel_hi:[1,0,1]
	v_pk_fma_f32 v[46:47], v[22:23], v[146:147], v[46:47] op_sel:[0,1,0] op_sel_hi:[1,1,1]
	v_pk_fma_f32 v[50:51], v[22:23], v[42:43], v[50:51] op_sel:[0,1,0] op_sel_hi:[1,1,1]
	ds_read_b128 v[40:43], v2 offset:512
	v_pk_mul_f32 v[168:169], v[164:165], v[156:157] op_sel_hi:[1,0]
	v_add_f32_dpp v48, v47, v46 quad_perm:[1,0,3,2] row_mask:0xf bank_mask:0xf bound_ctrl:1
	v_add_f32_dpp v52, v51, v50 quad_perm:[1,0,3,2] row_mask:0xf bank_mask:0xf bound_ctrl:1
	v_pk_mul_f32 v[170:171], v[164:165], v[156:157] op_sel:[0,1] op_sel_hi:[1,1]
	v_add_f32_dpp v48, v48, v48 quad_perm:[2,3,0,1] row_mask:0xf bank_mask:0xf bound_ctrl:1
	v_pk_mul_f32 v[172:173], v[164:165], v[158:159] op_sel_hi:[1,0]
	v_pk_mul_f32 v[174:175], v[164:165], v[158:159] op_sel:[0,1] op_sel_hi:[1,1]
	v_add_f32_dpp v48, v48, v48 row_ror:4 row_mask:0xf bank_mask:0xf bound_ctrl:1
	v_pk_fma_f32 v[168:169], v[16:17], v[148:149], v[168:169] op_sel_hi:[1,0,1]
	v_pk_fma_f32 v[170:171], v[18:19], v[148:149], v[170:171] op_sel:[0,1,0] op_sel_hi:[1,1,1]
	v_add_f32_dpp v48, v48, v48 row_ror:8 row_mask:0xf bank_mask:0xf bound_ctrl:1
	v_pk_fma_f32 v[172:173], v[20:21], v[150:151], v[172:173] op_sel_hi:[1,0,1]
	v_pk_fma_f32 v[174:175], v[22:23], v[150:151], v[174:175] op_sel:[0,1,0] op_sel_hi:[1,1,1]
	v_mov_b32_dpp v49, v48 quad_perm:[1,0,3,2] row_mask:0xf bank_mask:0xf bound_ctrl:1
	v_pk_fma_f32 v[16:17], v[48:49], v[152:153], v[168:169] op_sel_hi:[1,0,1] neg_lo:[0,1,0] neg_hi:[0,1,0]
	v_pk_fma_f32 v[18:19], v[48:49], v[152:153], v[170:171] op_sel:[0,1,0] op_sel_hi:[1,1,1] neg_lo:[0,1,0] neg_hi:[0,1,0]
	v_pk_fma_f32 v[20:21], v[48:49], v[154:155], v[172:173] op_sel_hi:[1,0,1] neg_lo:[0,1,0] neg_hi:[0,1,0]
	v_pk_fma_f32 v[22:23], v[48:49], v[154:155], v[174:175] op_sel:[0,1,0] op_sel_hi:[1,1,1] neg_lo:[0,1,0] neg_hi:[0,1,0]
	ds_read_b128 v[144:147], v2 offset:17152
	ds_read_b64 v[164:165], v3 offset:13056
	ds_read_b128 v[156:159], v2 offset:8960
	ds_read_b128 v[148:151], v2 offset:4864
	ds_read_b128 v[152:155], v2 offset:21248
	s_waitcnt lgkmcnt(5)
	v_pk_mul_f32 v[46:47], v[16:17], v[24:25] op_sel_hi:[1,0]
	v_pk_mul_f32 v[50:51], v[16:17], v[160:161] op_sel_hi:[1,0]
	v_pk_fma_f32 v[46:47], v[18:19], v[24:25], v[46:47] op_sel:[0,1,0] op_sel_hi:[1,1,1]
	v_pk_fma_f32 v[50:51], v[18:19], v[160:161], v[50:51] op_sel:[0,1,0] op_sel_hi:[1,1,1]
	v_pk_fma_f32 v[46:47], v[20:21], v[26:27], v[46:47] op_sel_hi:[1,0,1]
	v_pk_fma_f32 v[50:51], v[20:21], v[162:163], v[50:51] op_sel_hi:[1,0,1]
	v_pk_fma_f32 v[46:47], v[22:23], v[26:27], v[46:47] op_sel:[0,1,0] op_sel_hi:[1,1,1]
	v_pk_fma_f32 v[50:51], v[22:23], v[162:163], v[50:51] op_sel:[0,1,0] op_sel_hi:[1,1,1]
	ds_read_b128 v[160:163], v2 offset:768
	v_pk_mul_f32 v[168:169], v[44:45], v[36:37] op_sel_hi:[1,0]
	v_add_f32_dpp v48, v47, v46 quad_perm:[1,0,3,2] row_mask:0xf bank_mask:0xf bound_ctrl:1
	v_add_f32_dpp v53, v51, v50 quad_perm:[1,0,3,2] row_mask:0xf bank_mask:0xf bound_ctrl:1
	v_pk_mul_f32 v[170:171], v[44:45], v[36:37] op_sel:[0,1] op_sel_hi:[1,1]
	v_add_f32_dpp v48, v48, v48 quad_perm:[2,3,0,1] row_mask:0xf bank_mask:0xf bound_ctrl:1
	ds_write2st64_b32 v0, v52, v53 offset0:192 offset1:196
	v_pk_mul_f32 v[172:173], v[44:45], v[38:39] op_sel_hi:[1,0]
	v_pk_mul_f32 v[174:175], v[44:45], v[38:39] op_sel:[0,1] op_sel_hi:[1,1]
	v_add_f32_dpp v48, v48, v48 row_ror:4 row_mask:0xf bank_mask:0xf bound_ctrl:1
	v_pk_fma_f32 v[168:169], v[16:17], v[28:29], v[168:169] op_sel_hi:[1,0,1]
	v_pk_fma_f32 v[170:171], v[18:19], v[28:29], v[170:171] op_sel:[0,1,0] op_sel_hi:[1,1,1]
	v_add_f32_dpp v48, v48, v48 row_ror:8 row_mask:0xf bank_mask:0xf bound_ctrl:1
	v_pk_fma_f32 v[172:173], v[20:21], v[30:31], v[172:173] op_sel_hi:[1,0,1]
	v_pk_fma_f32 v[174:175], v[22:23], v[30:31], v[174:175] op_sel:[0,1,0] op_sel_hi:[1,1,1]
	v_mov_b32_dpp v49, v48 quad_perm:[1,0,3,2] row_mask:0xf bank_mask:0xf bound_ctrl:1
	v_pk_fma_f32 v[16:17], v[48:49], v[32:33], v[168:169] op_sel_hi:[1,0,1] neg_lo:[0,1,0] neg_hi:[0,1,0]
	v_pk_fma_f32 v[18:19], v[48:49], v[32:33], v[170:171] op_sel:[0,1,0] op_sel_hi:[1,1,1] neg_lo:[0,1,0] neg_hi:[0,1,0]
	v_pk_fma_f32 v[20:21], v[48:49], v[34:35], v[172:173] op_sel_hi:[1,0,1] neg_lo:[0,1,0] neg_hi:[0,1,0]
	v_pk_fma_f32 v[22:23], v[48:49], v[34:35], v[174:175] op_sel:[0,1,0] op_sel_hi:[1,1,1] neg_lo:[0,1,0] neg_hi:[0,1,0]
	ds_read_b128 v[24:27], v2 offset:17408
	ds_read_b64 v[44:45], v3 offset:13312
	ds_read_b128 v[36:39], v2 offset:9216
	ds_read_b128 v[28:31], v2 offset:5120
	ds_read_b128 v[32:35], v2 offset:21504
	s_waitcnt lgkmcnt(6)
	v_pk_mul_f32 v[46:47], v[16:17], v[144:145] op_sel_hi:[1,0]
	v_pk_mul_f32 v[50:51], v[16:17], v[40:41] op_sel_hi:[1,0]
	v_pk_fma_f32 v[46:47], v[18:19], v[144:145], v[46:47] op_sel:[0,1,0] op_sel_hi:[1,1,1]
	v_pk_fma_f32 v[50:51], v[18:19], v[40:41], v[50:51] op_sel:[0,1,0] op_sel_hi:[1,1,1]
	v_pk_fma_f32 v[46:47], v[20:21], v[146:147], v[46:47] op_sel_hi:[1,0,1]
	v_pk_fma_f32 v[50:51], v[20:21], v[42:43], v[50:51] op_sel_hi:[1,0,1]
	v_pk_fma_f32 v[46:47], v[22:23], v[146:147], v[46:47] op_sel:[0,1,0] op_sel_hi:[1,1,1]
	v_pk_fma_f32 v[50:51], v[22:23], v[42:43], v[50:51] op_sel:[0,1,0] op_sel_hi:[1,1,1]
	ds_read_b128 v[40:43], v2 offset:1024
	v_pk_mul_f32 v[168:169], v[164:165], v[156:157] op_sel_hi:[1,0]
	v_add_f32_dpp v48, v47, v46 quad_perm:[1,0,3,2] row_mask:0xf bank_mask:0xf bound_ctrl:1
	v_add_f32_dpp v52, v51, v50 quad_perm:[1,0,3,2] row_mask:0xf bank_mask:0xf bound_ctrl:1
	v_pk_mul_f32 v[170:171], v[164:165], v[156:157] op_sel:[0,1] op_sel_hi:[1,1]
	v_add_f32_dpp v48, v48, v48 quad_perm:[2,3,0,1] row_mask:0xf bank_mask:0xf bound_ctrl:1
	v_pk_mul_f32 v[172:173], v[164:165], v[158:159] op_sel_hi:[1,0]
	v_pk_mul_f32 v[174:175], v[164:165], v[158:159] op_sel:[0,1] op_sel_hi:[1,1]
	v_add_f32_dpp v48, v48, v48 row_ror:4 row_mask:0xf bank_mask:0xf bound_ctrl:1
	v_pk_fma_f32 v[168:169], v[16:17], v[148:149], v[168:169] op_sel_hi:[1,0,1]
	v_pk_fma_f32 v[170:171], v[18:19], v[148:149], v[170:171] op_sel:[0,1,0] op_sel_hi:[1,1,1]
	v_add_f32_dpp v48, v48, v48 row_ror:8 row_mask:0xf bank_mask:0xf bound_ctrl:1
	v_pk_fma_f32 v[172:173], v[20:21], v[150:151], v[172:173] op_sel_hi:[1,0,1]
	v_pk_fma_f32 v[174:175], v[22:23], v[150:151], v[174:175] op_sel:[0,1,0] op_sel_hi:[1,1,1]
	v_mov_b32_dpp v49, v48 quad_perm:[1,0,3,2] row_mask:0xf bank_mask:0xf bound_ctrl:1
	v_pk_fma_f32 v[16:17], v[48:49], v[152:153], v[168:169] op_sel_hi:[1,0,1] neg_lo:[0,1,0] neg_hi:[0,1,0]
	v_pk_fma_f32 v[18:19], v[48:49], v[152:153], v[170:171] op_sel:[0,1,0] op_sel_hi:[1,1,1] neg_lo:[0,1,0] neg_hi:[0,1,0]
	v_pk_fma_f32 v[20:21], v[48:49], v[154:155], v[172:173] op_sel_hi:[1,0,1] neg_lo:[0,1,0] neg_hi:[0,1,0]
	v_pk_fma_f32 v[22:23], v[48:49], v[154:155], v[174:175] op_sel:[0,1,0] op_sel_hi:[1,1,1] neg_lo:[0,1,0] neg_hi:[0,1,0]
	ds_read_b128 v[144:147], v2 offset:17664
	ds_read_b64 v[164:165], v3 offset:13568
	ds_read_b128 v[156:159], v2 offset:9472
	ds_read_b128 v[148:151], v2 offset:5376
	ds_read_b128 v[152:155], v2 offset:21760
	s_waitcnt lgkmcnt(5)
	v_pk_mul_f32 v[46:47], v[16:17], v[24:25] op_sel_hi:[1,0]
	v_pk_mul_f32 v[50:51], v[16:17], v[160:161] op_sel_hi:[1,0]
	v_pk_fma_f32 v[46:47], v[18:19], v[24:25], v[46:47] op_sel:[0,1,0] op_sel_hi:[1,1,1]
	v_pk_fma_f32 v[50:51], v[18:19], v[160:161], v[50:51] op_sel:[0,1,0] op_sel_hi:[1,1,1]
	v_pk_fma_f32 v[46:47], v[20:21], v[26:27], v[46:47] op_sel_hi:[1,0,1]
	v_pk_fma_f32 v[50:51], v[20:21], v[162:163], v[50:51] op_sel_hi:[1,0,1]
	v_pk_fma_f32 v[46:47], v[22:23], v[26:27], v[46:47] op_sel:[0,1,0] op_sel_hi:[1,1,1]
	v_pk_fma_f32 v[50:51], v[22:23], v[162:163], v[50:51] op_sel:[0,1,0] op_sel_hi:[1,1,1]
	ds_read_b128 v[160:163], v2 offset:1280
	v_pk_mul_f32 v[168:169], v[44:45], v[36:37] op_sel_hi:[1,0]
	v_add_f32_dpp v48, v47, v46 quad_perm:[1,0,3,2] row_mask:0xf bank_mask:0xf bound_ctrl:1
	v_add_f32_dpp v53, v51, v50 quad_perm:[1,0,3,2] row_mask:0xf bank_mask:0xf bound_ctrl:1
	v_pk_mul_f32 v[170:171], v[44:45], v[36:37] op_sel:[0,1] op_sel_hi:[1,1]
	v_add_f32_dpp v48, v48, v48 quad_perm:[2,3,0,1] row_mask:0xf bank_mask:0xf bound_ctrl:1
	ds_write2st64_b32 v0, v52, v53 offset0:200 offset1:204
	v_pk_mul_f32 v[172:173], v[44:45], v[38:39] op_sel_hi:[1,0]
	v_pk_mul_f32 v[174:175], v[44:45], v[38:39] op_sel:[0,1] op_sel_hi:[1,1]
	v_add_f32_dpp v48, v48, v48 row_ror:4 row_mask:0xf bank_mask:0xf bound_ctrl:1
	v_pk_fma_f32 v[168:169], v[16:17], v[28:29], v[168:169] op_sel_hi:[1,0,1]
	v_pk_fma_f32 v[170:171], v[18:19], v[28:29], v[170:171] op_sel:[0,1,0] op_sel_hi:[1,1,1]
	v_add_f32_dpp v48, v48, v48 row_ror:8 row_mask:0xf bank_mask:0xf bound_ctrl:1
	v_pk_fma_f32 v[172:173], v[20:21], v[30:31], v[172:173] op_sel_hi:[1,0,1]
	v_pk_fma_f32 v[174:175], v[22:23], v[30:31], v[174:175] op_sel:[0,1,0] op_sel_hi:[1,1,1]
	v_mov_b32_dpp v49, v48 quad_perm:[1,0,3,2] row_mask:0xf bank_mask:0xf bound_ctrl:1
	v_pk_fma_f32 v[16:17], v[48:49], v[32:33], v[168:169] op_sel_hi:[1,0,1] neg_lo:[0,1,0] neg_hi:[0,1,0]
	v_pk_fma_f32 v[18:19], v[48:49], v[32:33], v[170:171] op_sel:[0,1,0] op_sel_hi:[1,1,1] neg_lo:[0,1,0] neg_hi:[0,1,0]
	v_pk_fma_f32 v[20:21], v[48:49], v[34:35], v[172:173] op_sel_hi:[1,0,1] neg_lo:[0,1,0] neg_hi:[0,1,0]
	v_pk_fma_f32 v[22:23], v[48:49], v[34:35], v[174:175] op_sel:[0,1,0] op_sel_hi:[1,1,1] neg_lo:[0,1,0] neg_hi:[0,1,0]
	ds_read_b128 v[24:27], v2 offset:17920
	ds_read_b64 v[44:45], v3 offset:13824
	ds_read_b128 v[36:39], v2 offset:9728
	ds_read_b128 v[28:31], v2 offset:5632
	ds_read_b128 v[32:35], v2 offset:22016
	s_waitcnt lgkmcnt(6)
	v_pk_mul_f32 v[46:47], v[16:17], v[144:145] op_sel_hi:[1,0]
	v_pk_mul_f32 v[50:51], v[16:17], v[40:41] op_sel_hi:[1,0]
	v_pk_fma_f32 v[46:47], v[18:19], v[144:145], v[46:47] op_sel:[0,1,0] op_sel_hi:[1,1,1]
	v_pk_fma_f32 v[50:51], v[18:19], v[40:41], v[50:51] op_sel:[0,1,0] op_sel_hi:[1,1,1]
	v_pk_fma_f32 v[46:47], v[20:21], v[146:147], v[46:47] op_sel_hi:[1,0,1]
	v_pk_fma_f32 v[50:51], v[20:21], v[42:43], v[50:51] op_sel_hi:[1,0,1]
	v_pk_fma_f32 v[46:47], v[22:23], v[146:147], v[46:47] op_sel:[0,1,0] op_sel_hi:[1,1,1]
	v_pk_fma_f32 v[50:51], v[22:23], v[42:43], v[50:51] op_sel:[0,1,0] op_sel_hi:[1,1,1]
	ds_read_b128 v[40:43], v2 offset:1536
	v_pk_mul_f32 v[168:169], v[164:165], v[156:157] op_sel_hi:[1,0]
	v_add_f32_dpp v48, v47, v46 quad_perm:[1,0,3,2] row_mask:0xf bank_mask:0xf bound_ctrl:1
	v_add_f32_dpp v52, v51, v50 quad_perm:[1,0,3,2] row_mask:0xf bank_mask:0xf bound_ctrl:1
	v_pk_mul_f32 v[170:171], v[164:165], v[156:157] op_sel:[0,1] op_sel_hi:[1,1]
	v_add_f32_dpp v48, v48, v48 quad_perm:[2,3,0,1] row_mask:0xf bank_mask:0xf bound_ctrl:1
	v_pk_mul_f32 v[172:173], v[164:165], v[158:159] op_sel_hi:[1,0]
	v_pk_mul_f32 v[174:175], v[164:165], v[158:159] op_sel:[0,1] op_sel_hi:[1,1]
	v_add_f32_dpp v48, v48, v48 row_ror:4 row_mask:0xf bank_mask:0xf bound_ctrl:1
	v_pk_fma_f32 v[168:169], v[16:17], v[148:149], v[168:169] op_sel_hi:[1,0,1]
	v_pk_fma_f32 v[170:171], v[18:19], v[148:149], v[170:171] op_sel:[0,1,0] op_sel_hi:[1,1,1]
	v_add_f32_dpp v48, v48, v48 row_ror:8 row_mask:0xf bank_mask:0xf bound_ctrl:1
	v_pk_fma_f32 v[172:173], v[20:21], v[150:151], v[172:173] op_sel_hi:[1,0,1]
	v_pk_fma_f32 v[174:175], v[22:23], v[150:151], v[174:175] op_sel:[0,1,0] op_sel_hi:[1,1,1]
	v_mov_b32_dpp v49, v48 quad_perm:[1,0,3,2] row_mask:0xf bank_mask:0xf bound_ctrl:1
	v_pk_fma_f32 v[16:17], v[48:49], v[152:153], v[168:169] op_sel_hi:[1,0,1] neg_lo:[0,1,0] neg_hi:[0,1,0]
	v_pk_fma_f32 v[18:19], v[48:49], v[152:153], v[170:171] op_sel:[0,1,0] op_sel_hi:[1,1,1] neg_lo:[0,1,0] neg_hi:[0,1,0]
	v_pk_fma_f32 v[20:21], v[48:49], v[154:155], v[172:173] op_sel_hi:[1,0,1] neg_lo:[0,1,0] neg_hi:[0,1,0]
	v_pk_fma_f32 v[22:23], v[48:49], v[154:155], v[174:175] op_sel:[0,1,0] op_sel_hi:[1,1,1] neg_lo:[0,1,0] neg_hi:[0,1,0]
	ds_read_b128 v[144:147], v2 offset:18176
	ds_read_b64 v[164:165], v3 offset:14080
	ds_read_b128 v[156:159], v2 offset:9984
	ds_read_b128 v[148:151], v2 offset:5888
	ds_read_b128 v[152:155], v2 offset:22272
	s_waitcnt lgkmcnt(5)
	v_pk_mul_f32 v[46:47], v[16:17], v[24:25] op_sel_hi:[1,0]
	v_pk_mul_f32 v[50:51], v[16:17], v[160:161] op_sel_hi:[1,0]
	v_pk_fma_f32 v[46:47], v[18:19], v[24:25], v[46:47] op_sel:[0,1,0] op_sel_hi:[1,1,1]
	v_pk_fma_f32 v[50:51], v[18:19], v[160:161], v[50:51] op_sel:[0,1,0] op_sel_hi:[1,1,1]
	v_pk_fma_f32 v[46:47], v[20:21], v[26:27], v[46:47] op_sel_hi:[1,0,1]
	v_pk_fma_f32 v[50:51], v[20:21], v[162:163], v[50:51] op_sel_hi:[1,0,1]
	v_pk_fma_f32 v[46:47], v[22:23], v[26:27], v[46:47] op_sel:[0,1,0] op_sel_hi:[1,1,1]
	v_pk_fma_f32 v[50:51], v[22:23], v[162:163], v[50:51] op_sel:[0,1,0] op_sel_hi:[1,1,1]
	ds_read_b128 v[160:163], v2 offset:1792
	v_pk_mul_f32 v[168:169], v[44:45], v[36:37] op_sel_hi:[1,0]
	v_add_f32_dpp v48, v47, v46 quad_perm:[1,0,3,2] row_mask:0xf bank_mask:0xf bound_ctrl:1
	v_add_f32_dpp v53, v51, v50 quad_perm:[1,0,3,2] row_mask:0xf bank_mask:0xf bound_ctrl:1
	v_pk_mul_f32 v[170:171], v[44:45], v[36:37] op_sel:[0,1] op_sel_hi:[1,1]
	v_add_f32_dpp v48, v48, v48 quad_perm:[2,3,0,1] row_mask:0xf bank_mask:0xf bound_ctrl:1
	ds_write2st64_b32 v0, v52, v53 offset0:208 offset1:212
	v_pk_mul_f32 v[172:173], v[44:45], v[38:39] op_sel_hi:[1,0]
	v_pk_mul_f32 v[174:175], v[44:45], v[38:39] op_sel:[0,1] op_sel_hi:[1,1]
	v_add_f32_dpp v48, v48, v48 row_ror:4 row_mask:0xf bank_mask:0xf bound_ctrl:1
	v_pk_fma_f32 v[168:169], v[16:17], v[28:29], v[168:169] op_sel_hi:[1,0,1]
	v_pk_fma_f32 v[170:171], v[18:19], v[28:29], v[170:171] op_sel:[0,1,0] op_sel_hi:[1,1,1]
	v_add_f32_dpp v48, v48, v48 row_ror:8 row_mask:0xf bank_mask:0xf bound_ctrl:1
	v_pk_fma_f32 v[172:173], v[20:21], v[30:31], v[172:173] op_sel_hi:[1,0,1]
	v_pk_fma_f32 v[174:175], v[22:23], v[30:31], v[174:175] op_sel:[0,1,0] op_sel_hi:[1,1,1]
	v_mov_b32_dpp v49, v48 quad_perm:[1,0,3,2] row_mask:0xf bank_mask:0xf bound_ctrl:1
	v_pk_fma_f32 v[16:17], v[48:49], v[32:33], v[168:169] op_sel_hi:[1,0,1] neg_lo:[0,1,0] neg_hi:[0,1,0]
	v_pk_fma_f32 v[18:19], v[48:49], v[32:33], v[170:171] op_sel:[0,1,0] op_sel_hi:[1,1,1] neg_lo:[0,1,0] neg_hi:[0,1,0]
	v_pk_fma_f32 v[20:21], v[48:49], v[34:35], v[172:173] op_sel_hi:[1,0,1] neg_lo:[0,1,0] neg_hi:[0,1,0]
	v_pk_fma_f32 v[22:23], v[48:49], v[34:35], v[174:175] op_sel:[0,1,0] op_sel_hi:[1,1,1] neg_lo:[0,1,0] neg_hi:[0,1,0]
	ds_read_b128 v[24:27], v2 offset:18432
	ds_read_b64 v[44:45], v3 offset:14336
	ds_read_b128 v[36:39], v2 offset:10240
	ds_read_b128 v[28:31], v2 offset:6144
	ds_read_b128 v[32:35], v2 offset:22528
	s_waitcnt lgkmcnt(6)
	v_pk_mul_f32 v[46:47], v[16:17], v[144:145] op_sel_hi:[1,0]
	v_pk_mul_f32 v[50:51], v[16:17], v[40:41] op_sel_hi:[1,0]
	v_pk_fma_f32 v[46:47], v[18:19], v[144:145], v[46:47] op_sel:[0,1,0] op_sel_hi:[1,1,1]
	v_pk_fma_f32 v[50:51], v[18:19], v[40:41], v[50:51] op_sel:[0,1,0] op_sel_hi:[1,1,1]
	v_pk_fma_f32 v[46:47], v[20:21], v[146:147], v[46:47] op_sel_hi:[1,0,1]
	v_pk_fma_f32 v[50:51], v[20:21], v[42:43], v[50:51] op_sel_hi:[1,0,1]
	v_pk_fma_f32 v[46:47], v[22:23], v[146:147], v[46:47] op_sel:[0,1,0] op_sel_hi:[1,1,1]
	v_pk_fma_f32 v[50:51], v[22:23], v[42:43], v[50:51] op_sel:[0,1,0] op_sel_hi:[1,1,1]
	ds_read_b128 v[40:43], v2 offset:2048
	v_pk_mul_f32 v[168:169], v[164:165], v[156:157] op_sel_hi:[1,0]
	v_add_f32_dpp v48, v47, v46 quad_perm:[1,0,3,2] row_mask:0xf bank_mask:0xf bound_ctrl:1
	v_add_f32_dpp v52, v51, v50 quad_perm:[1,0,3,2] row_mask:0xf bank_mask:0xf bound_ctrl:1
	v_pk_mul_f32 v[170:171], v[164:165], v[156:157] op_sel:[0,1] op_sel_hi:[1,1]
	v_add_f32_dpp v48, v48, v48 quad_perm:[2,3,0,1] row_mask:0xf bank_mask:0xf bound_ctrl:1
	v_pk_mul_f32 v[172:173], v[164:165], v[158:159] op_sel_hi:[1,0]
	v_pk_mul_f32 v[174:175], v[164:165], v[158:159] op_sel:[0,1] op_sel_hi:[1,1]
	v_add_f32_dpp v48, v48, v48 row_ror:4 row_mask:0xf bank_mask:0xf bound_ctrl:1
	v_pk_fma_f32 v[168:169], v[16:17], v[148:149], v[168:169] op_sel_hi:[1,0,1]
	v_pk_fma_f32 v[170:171], v[18:19], v[148:149], v[170:171] op_sel:[0,1,0] op_sel_hi:[1,1,1]
	v_add_f32_dpp v48, v48, v48 row_ror:8 row_mask:0xf bank_mask:0xf bound_ctrl:1
	v_pk_fma_f32 v[172:173], v[20:21], v[150:151], v[172:173] op_sel_hi:[1,0,1]
	v_pk_fma_f32 v[174:175], v[22:23], v[150:151], v[174:175] op_sel:[0,1,0] op_sel_hi:[1,1,1]
	v_mov_b32_dpp v49, v48 quad_perm:[1,0,3,2] row_mask:0xf bank_mask:0xf bound_ctrl:1
	v_pk_fma_f32 v[16:17], v[48:49], v[152:153], v[168:169] op_sel_hi:[1,0,1] neg_lo:[0,1,0] neg_hi:[0,1,0]
	v_pk_fma_f32 v[18:19], v[48:49], v[152:153], v[170:171] op_sel:[0,1,0] op_sel_hi:[1,1,1] neg_lo:[0,1,0] neg_hi:[0,1,0]
	v_pk_fma_f32 v[20:21], v[48:49], v[154:155], v[172:173] op_sel_hi:[1,0,1] neg_lo:[0,1,0] neg_hi:[0,1,0]
	v_pk_fma_f32 v[22:23], v[48:49], v[154:155], v[174:175] op_sel:[0,1,0] op_sel_hi:[1,1,1] neg_lo:[0,1,0] neg_hi:[0,1,0]
	ds_read_b128 v[144:147], v2 offset:18688
	ds_read_b64 v[164:165], v3 offset:14592
	ds_read_b128 v[156:159], v2 offset:10496
	ds_read_b128 v[148:151], v2 offset:6400
	ds_read_b128 v[152:155], v2 offset:22784
	s_waitcnt lgkmcnt(5)
	v_pk_mul_f32 v[46:47], v[16:17], v[24:25] op_sel_hi:[1,0]
	v_pk_mul_f32 v[50:51], v[16:17], v[160:161] op_sel_hi:[1,0]
	v_pk_fma_f32 v[46:47], v[18:19], v[24:25], v[46:47] op_sel:[0,1,0] op_sel_hi:[1,1,1]
	v_pk_fma_f32 v[50:51], v[18:19], v[160:161], v[50:51] op_sel:[0,1,0] op_sel_hi:[1,1,1]
	v_pk_fma_f32 v[46:47], v[20:21], v[26:27], v[46:47] op_sel_hi:[1,0,1]
	v_pk_fma_f32 v[50:51], v[20:21], v[162:163], v[50:51] op_sel_hi:[1,0,1]
	v_pk_fma_f32 v[46:47], v[22:23], v[26:27], v[46:47] op_sel:[0,1,0] op_sel_hi:[1,1,1]
	v_pk_fma_f32 v[50:51], v[22:23], v[162:163], v[50:51] op_sel:[0,1,0] op_sel_hi:[1,1,1]
	ds_read_b128 v[160:163], v2 offset:2304
	v_pk_mul_f32 v[168:169], v[44:45], v[36:37] op_sel_hi:[1,0]
	v_add_f32_dpp v48, v47, v46 quad_perm:[1,0,3,2] row_mask:0xf bank_mask:0xf bound_ctrl:1
	v_add_f32_dpp v53, v51, v50 quad_perm:[1,0,3,2] row_mask:0xf bank_mask:0xf bound_ctrl:1
	v_pk_mul_f32 v[170:171], v[44:45], v[36:37] op_sel:[0,1] op_sel_hi:[1,1]
	v_add_f32_dpp v48, v48, v48 quad_perm:[2,3,0,1] row_mask:0xf bank_mask:0xf bound_ctrl:1
	ds_write2st64_b32 v0, v52, v53 offset0:216 offset1:220
	v_pk_mul_f32 v[172:173], v[44:45], v[38:39] op_sel_hi:[1,0]
	v_pk_mul_f32 v[174:175], v[44:45], v[38:39] op_sel:[0,1] op_sel_hi:[1,1]
	v_add_f32_dpp v48, v48, v48 row_ror:4 row_mask:0xf bank_mask:0xf bound_ctrl:1
	v_pk_fma_f32 v[168:169], v[16:17], v[28:29], v[168:169] op_sel_hi:[1,0,1]
	v_pk_fma_f32 v[170:171], v[18:19], v[28:29], v[170:171] op_sel:[0,1,0] op_sel_hi:[1,1,1]
	v_add_f32_dpp v48, v48, v48 row_ror:8 row_mask:0xf bank_mask:0xf bound_ctrl:1
	v_pk_fma_f32 v[172:173], v[20:21], v[30:31], v[172:173] op_sel_hi:[1,0,1]
	v_pk_fma_f32 v[174:175], v[22:23], v[30:31], v[174:175] op_sel:[0,1,0] op_sel_hi:[1,1,1]
	v_mov_b32_dpp v49, v48 quad_perm:[1,0,3,2] row_mask:0xf bank_mask:0xf bound_ctrl:1
	v_pk_fma_f32 v[16:17], v[48:49], v[32:33], v[168:169] op_sel_hi:[1,0,1] neg_lo:[0,1,0] neg_hi:[0,1,0]
	v_pk_fma_f32 v[18:19], v[48:49], v[32:33], v[170:171] op_sel:[0,1,0] op_sel_hi:[1,1,1] neg_lo:[0,1,0] neg_hi:[0,1,0]
	v_pk_fma_f32 v[20:21], v[48:49], v[34:35], v[172:173] op_sel_hi:[1,0,1] neg_lo:[0,1,0] neg_hi:[0,1,0]
	v_pk_fma_f32 v[22:23], v[48:49], v[34:35], v[174:175] op_sel:[0,1,0] op_sel_hi:[1,1,1] neg_lo:[0,1,0] neg_hi:[0,1,0]
	ds_read_b128 v[24:27], v2 offset:18944
	ds_read_b64 v[44:45], v3 offset:14848
	ds_read_b128 v[36:39], v2 offset:10752
	ds_read_b128 v[28:31], v2 offset:6656
	ds_read_b128 v[32:35], v2 offset:23040
	s_waitcnt lgkmcnt(6)
	v_pk_mul_f32 v[46:47], v[16:17], v[144:145] op_sel_hi:[1,0]
	v_pk_mul_f32 v[50:51], v[16:17], v[40:41] op_sel_hi:[1,0]
	v_pk_fma_f32 v[46:47], v[18:19], v[144:145], v[46:47] op_sel:[0,1,0] op_sel_hi:[1,1,1]
	v_pk_fma_f32 v[50:51], v[18:19], v[40:41], v[50:51] op_sel:[0,1,0] op_sel_hi:[1,1,1]
	v_pk_fma_f32 v[46:47], v[20:21], v[146:147], v[46:47] op_sel_hi:[1,0,1]
	v_pk_fma_f32 v[50:51], v[20:21], v[42:43], v[50:51] op_sel_hi:[1,0,1]
	v_pk_fma_f32 v[46:47], v[22:23], v[146:147], v[46:47] op_sel:[0,1,0] op_sel_hi:[1,1,1]
	v_pk_fma_f32 v[50:51], v[22:23], v[42:43], v[50:51] op_sel:[0,1,0] op_sel_hi:[1,1,1]
	ds_read_b128 v[40:43], v2 offset:2560
	v_pk_mul_f32 v[168:169], v[164:165], v[156:157] op_sel_hi:[1,0]
	v_add_f32_dpp v48, v47, v46 quad_perm:[1,0,3,2] row_mask:0xf bank_mask:0xf bound_ctrl:1
	v_add_f32_dpp v52, v51, v50 quad_perm:[1,0,3,2] row_mask:0xf bank_mask:0xf bound_ctrl:1
	v_pk_mul_f32 v[170:171], v[164:165], v[156:157] op_sel:[0,1] op_sel_hi:[1,1]
	v_add_f32_dpp v48, v48, v48 quad_perm:[2,3,0,1] row_mask:0xf bank_mask:0xf bound_ctrl:1
	v_pk_mul_f32 v[172:173], v[164:165], v[158:159] op_sel_hi:[1,0]
	v_pk_mul_f32 v[174:175], v[164:165], v[158:159] op_sel:[0,1] op_sel_hi:[1,1]
	v_add_f32_dpp v48, v48, v48 row_ror:4 row_mask:0xf bank_mask:0xf bound_ctrl:1
	v_pk_fma_f32 v[168:169], v[16:17], v[148:149], v[168:169] op_sel_hi:[1,0,1]
	v_pk_fma_f32 v[170:171], v[18:19], v[148:149], v[170:171] op_sel:[0,1,0] op_sel_hi:[1,1,1]
	v_add_f32_dpp v48, v48, v48 row_ror:8 row_mask:0xf bank_mask:0xf bound_ctrl:1
	v_pk_fma_f32 v[172:173], v[20:21], v[150:151], v[172:173] op_sel_hi:[1,0,1]
	v_pk_fma_f32 v[174:175], v[22:23], v[150:151], v[174:175] op_sel:[0,1,0] op_sel_hi:[1,1,1]
	v_mov_b32_dpp v49, v48 quad_perm:[1,0,3,2] row_mask:0xf bank_mask:0xf bound_ctrl:1
	v_pk_fma_f32 v[16:17], v[48:49], v[152:153], v[168:169] op_sel_hi:[1,0,1] neg_lo:[0,1,0] neg_hi:[0,1,0]
	v_pk_fma_f32 v[18:19], v[48:49], v[152:153], v[170:171] op_sel:[0,1,0] op_sel_hi:[1,1,1] neg_lo:[0,1,0] neg_hi:[0,1,0]
	v_pk_fma_f32 v[20:21], v[48:49], v[154:155], v[172:173] op_sel_hi:[1,0,1] neg_lo:[0,1,0] neg_hi:[0,1,0]
	v_pk_fma_f32 v[22:23], v[48:49], v[154:155], v[174:175] op_sel:[0,1,0] op_sel_hi:[1,1,1] neg_lo:[0,1,0] neg_hi:[0,1,0]
	ds_read_b128 v[144:147], v2 offset:19200
	ds_read_b64 v[164:165], v3 offset:15104
	ds_read_b128 v[156:159], v2 offset:11008
	ds_read_b128 v[148:151], v2 offset:6912
	ds_read_b128 v[152:155], v2 offset:23296
	s_waitcnt lgkmcnt(5)
	v_pk_mul_f32 v[46:47], v[16:17], v[24:25] op_sel_hi:[1,0]
	v_pk_mul_f32 v[50:51], v[16:17], v[160:161] op_sel_hi:[1,0]
	v_pk_fma_f32 v[46:47], v[18:19], v[24:25], v[46:47] op_sel:[0,1,0] op_sel_hi:[1,1,1]
	v_pk_fma_f32 v[50:51], v[18:19], v[160:161], v[50:51] op_sel:[0,1,0] op_sel_hi:[1,1,1]
	v_pk_fma_f32 v[46:47], v[20:21], v[26:27], v[46:47] op_sel_hi:[1,0,1]
	v_pk_fma_f32 v[50:51], v[20:21], v[162:163], v[50:51] op_sel_hi:[1,0,1]
	v_pk_fma_f32 v[46:47], v[22:23], v[26:27], v[46:47] op_sel:[0,1,0] op_sel_hi:[1,1,1]
	v_pk_fma_f32 v[50:51], v[22:23], v[162:163], v[50:51] op_sel:[0,1,0] op_sel_hi:[1,1,1]
	ds_read_b128 v[160:163], v2 offset:2816
	v_pk_mul_f32 v[168:169], v[44:45], v[36:37] op_sel_hi:[1,0]
	v_add_f32_dpp v48, v47, v46 quad_perm:[1,0,3,2] row_mask:0xf bank_mask:0xf bound_ctrl:1
	v_add_f32_dpp v53, v51, v50 quad_perm:[1,0,3,2] row_mask:0xf bank_mask:0xf bound_ctrl:1
	v_pk_mul_f32 v[170:171], v[44:45], v[36:37] op_sel:[0,1] op_sel_hi:[1,1]
	v_add_f32_dpp v48, v48, v48 quad_perm:[2,3,0,1] row_mask:0xf bank_mask:0xf bound_ctrl:1
	ds_write2st64_b32 v0, v52, v53 offset0:224 offset1:228
	v_pk_mul_f32 v[172:173], v[44:45], v[38:39] op_sel_hi:[1,0]
	v_pk_mul_f32 v[174:175], v[44:45], v[38:39] op_sel:[0,1] op_sel_hi:[1,1]
	v_add_f32_dpp v48, v48, v48 row_ror:4 row_mask:0xf bank_mask:0xf bound_ctrl:1
	v_pk_fma_f32 v[168:169], v[16:17], v[28:29], v[168:169] op_sel_hi:[1,0,1]
	v_pk_fma_f32 v[170:171], v[18:19], v[28:29], v[170:171] op_sel:[0,1,0] op_sel_hi:[1,1,1]
	v_add_f32_dpp v48, v48, v48 row_ror:8 row_mask:0xf bank_mask:0xf bound_ctrl:1
	v_pk_fma_f32 v[172:173], v[20:21], v[30:31], v[172:173] op_sel_hi:[1,0,1]
	v_pk_fma_f32 v[174:175], v[22:23], v[30:31], v[174:175] op_sel:[0,1,0] op_sel_hi:[1,1,1]
	v_mov_b32_dpp v49, v48 quad_perm:[1,0,3,2] row_mask:0xf bank_mask:0xf bound_ctrl:1
	v_pk_fma_f32 v[16:17], v[48:49], v[32:33], v[168:169] op_sel_hi:[1,0,1] neg_lo:[0,1,0] neg_hi:[0,1,0]
	v_pk_fma_f32 v[18:19], v[48:49], v[32:33], v[170:171] op_sel:[0,1,0] op_sel_hi:[1,1,1] neg_lo:[0,1,0] neg_hi:[0,1,0]
	v_pk_fma_f32 v[20:21], v[48:49], v[34:35], v[172:173] op_sel_hi:[1,0,1] neg_lo:[0,1,0] neg_hi:[0,1,0]
	v_pk_fma_f32 v[22:23], v[48:49], v[34:35], v[174:175] op_sel:[0,1,0] op_sel_hi:[1,1,1] neg_lo:[0,1,0] neg_hi:[0,1,0]
	ds_read_b128 v[24:27], v2 offset:19456
	ds_read_b64 v[44:45], v3 offset:15360
	ds_read_b128 v[36:39], v2 offset:11264
	ds_read_b128 v[28:31], v2 offset:7168
	ds_read_b128 v[32:35], v2 offset:23552
	s_waitcnt lgkmcnt(6)
	v_pk_mul_f32 v[46:47], v[16:17], v[144:145] op_sel_hi:[1,0]
	v_pk_mul_f32 v[50:51], v[16:17], v[40:41] op_sel_hi:[1,0]
	v_pk_fma_f32 v[46:47], v[18:19], v[144:145], v[46:47] op_sel:[0,1,0] op_sel_hi:[1,1,1]
	v_pk_fma_f32 v[50:51], v[18:19], v[40:41], v[50:51] op_sel:[0,1,0] op_sel_hi:[1,1,1]
	v_pk_fma_f32 v[46:47], v[20:21], v[146:147], v[46:47] op_sel_hi:[1,0,1]
	v_pk_fma_f32 v[50:51], v[20:21], v[42:43], v[50:51] op_sel_hi:[1,0,1]
	v_pk_fma_f32 v[46:47], v[22:23], v[146:147], v[46:47] op_sel:[0,1,0] op_sel_hi:[1,1,1]
	v_pk_fma_f32 v[50:51], v[22:23], v[42:43], v[50:51] op_sel:[0,1,0] op_sel_hi:[1,1,1]
	ds_read_b128 v[40:43], v2 offset:3072
	v_pk_mul_f32 v[168:169], v[164:165], v[156:157] op_sel_hi:[1,0]
	v_add_f32_dpp v48, v47, v46 quad_perm:[1,0,3,2] row_mask:0xf bank_mask:0xf bound_ctrl:1
	v_add_f32_dpp v52, v51, v50 quad_perm:[1,0,3,2] row_mask:0xf bank_mask:0xf bound_ctrl:1
	v_pk_mul_f32 v[170:171], v[164:165], v[156:157] op_sel:[0,1] op_sel_hi:[1,1]
	v_add_f32_dpp v48, v48, v48 quad_perm:[2,3,0,1] row_mask:0xf bank_mask:0xf bound_ctrl:1
	v_pk_mul_f32 v[172:173], v[164:165], v[158:159] op_sel_hi:[1,0]
	v_pk_mul_f32 v[174:175], v[164:165], v[158:159] op_sel:[0,1] op_sel_hi:[1,1]
	v_add_f32_dpp v48, v48, v48 row_ror:4 row_mask:0xf bank_mask:0xf bound_ctrl:1
	v_pk_fma_f32 v[168:169], v[16:17], v[148:149], v[168:169] op_sel_hi:[1,0,1]
	v_pk_fma_f32 v[170:171], v[18:19], v[148:149], v[170:171] op_sel:[0,1,0] op_sel_hi:[1,1,1]
	v_add_f32_dpp v48, v48, v48 row_ror:8 row_mask:0xf bank_mask:0xf bound_ctrl:1
	v_pk_fma_f32 v[172:173], v[20:21], v[150:151], v[172:173] op_sel_hi:[1,0,1]
	v_pk_fma_f32 v[174:175], v[22:23], v[150:151], v[174:175] op_sel:[0,1,0] op_sel_hi:[1,1,1]
	v_mov_b32_dpp v49, v48 quad_perm:[1,0,3,2] row_mask:0xf bank_mask:0xf bound_ctrl:1
	v_pk_fma_f32 v[16:17], v[48:49], v[152:153], v[168:169] op_sel_hi:[1,0,1] neg_lo:[0,1,0] neg_hi:[0,1,0]
	v_pk_fma_f32 v[18:19], v[48:49], v[152:153], v[170:171] op_sel:[0,1,0] op_sel_hi:[1,1,1] neg_lo:[0,1,0] neg_hi:[0,1,0]
	v_pk_fma_f32 v[20:21], v[48:49], v[154:155], v[172:173] op_sel_hi:[1,0,1] neg_lo:[0,1,0] neg_hi:[0,1,0]
	v_pk_fma_f32 v[22:23], v[48:49], v[154:155], v[174:175] op_sel:[0,1,0] op_sel_hi:[1,1,1] neg_lo:[0,1,0] neg_hi:[0,1,0]
	ds_read_b128 v[144:147], v2 offset:19712
	ds_read_b64 v[164:165], v3 offset:15616
	ds_read_b128 v[156:159], v2 offset:11520
	ds_read_b128 v[148:151], v2 offset:7424
	ds_read_b128 v[152:155], v2 offset:23808
	s_waitcnt lgkmcnt(5)
	v_pk_mul_f32 v[46:47], v[16:17], v[24:25] op_sel_hi:[1,0]
	v_pk_mul_f32 v[50:51], v[16:17], v[160:161] op_sel_hi:[1,0]
	v_pk_fma_f32 v[46:47], v[18:19], v[24:25], v[46:47] op_sel:[0,1,0] op_sel_hi:[1,1,1]
	v_pk_fma_f32 v[50:51], v[18:19], v[160:161], v[50:51] op_sel:[0,1,0] op_sel_hi:[1,1,1]
	v_pk_fma_f32 v[46:47], v[20:21], v[26:27], v[46:47] op_sel_hi:[1,0,1]
	v_pk_fma_f32 v[50:51], v[20:21], v[162:163], v[50:51] op_sel_hi:[1,0,1]
	v_pk_fma_f32 v[46:47], v[22:23], v[26:27], v[46:47] op_sel:[0,1,0] op_sel_hi:[1,1,1]
	v_pk_fma_f32 v[50:51], v[22:23], v[162:163], v[50:51] op_sel:[0,1,0] op_sel_hi:[1,1,1]
	ds_read_b128 v[160:163], v2 offset:3328
	v_pk_mul_f32 v[168:169], v[44:45], v[36:37] op_sel_hi:[1,0]
	v_add_f32_dpp v48, v47, v46 quad_perm:[1,0,3,2] row_mask:0xf bank_mask:0xf bound_ctrl:1
	v_add_f32_dpp v53, v51, v50 quad_perm:[1,0,3,2] row_mask:0xf bank_mask:0xf bound_ctrl:1
	v_pk_mul_f32 v[170:171], v[44:45], v[36:37] op_sel:[0,1] op_sel_hi:[1,1]
	v_add_f32_dpp v48, v48, v48 quad_perm:[2,3,0,1] row_mask:0xf bank_mask:0xf bound_ctrl:1
	ds_write2st64_b32 v0, v52, v53 offset0:232 offset1:236
	v_pk_mul_f32 v[172:173], v[44:45], v[38:39] op_sel_hi:[1,0]
	v_pk_mul_f32 v[174:175], v[44:45], v[38:39] op_sel:[0,1] op_sel_hi:[1,1]
	v_add_f32_dpp v48, v48, v48 row_ror:4 row_mask:0xf bank_mask:0xf bound_ctrl:1
	v_pk_fma_f32 v[168:169], v[16:17], v[28:29], v[168:169] op_sel_hi:[1,0,1]
	v_pk_fma_f32 v[170:171], v[18:19], v[28:29], v[170:171] op_sel:[0,1,0] op_sel_hi:[1,1,1]
	v_add_f32_dpp v48, v48, v48 row_ror:8 row_mask:0xf bank_mask:0xf bound_ctrl:1
	v_pk_fma_f32 v[172:173], v[20:21], v[30:31], v[172:173] op_sel_hi:[1,0,1]
	v_pk_fma_f32 v[174:175], v[22:23], v[30:31], v[174:175] op_sel:[0,1,0] op_sel_hi:[1,1,1]
	v_mov_b32_dpp v49, v48 quad_perm:[1,0,3,2] row_mask:0xf bank_mask:0xf bound_ctrl:1
	v_pk_fma_f32 v[16:17], v[48:49], v[32:33], v[168:169] op_sel_hi:[1,0,1] neg_lo:[0,1,0] neg_hi:[0,1,0]
	v_pk_fma_f32 v[18:19], v[48:49], v[32:33], v[170:171] op_sel:[0,1,0] op_sel_hi:[1,1,1] neg_lo:[0,1,0] neg_hi:[0,1,0]
	v_pk_fma_f32 v[20:21], v[48:49], v[34:35], v[172:173] op_sel_hi:[1,0,1] neg_lo:[0,1,0] neg_hi:[0,1,0]
	v_pk_fma_f32 v[22:23], v[48:49], v[34:35], v[174:175] op_sel:[0,1,0] op_sel_hi:[1,1,1] neg_lo:[0,1,0] neg_hi:[0,1,0]
	ds_read_b128 v[24:27], v2 offset:19968
	ds_read_b64 v[44:45], v3 offset:15872
	ds_read_b128 v[36:39], v2 offset:11776
	ds_read_b128 v[28:31], v2 offset:7680
	ds_read_b128 v[32:35], v2 offset:24064
	s_waitcnt lgkmcnt(6)
	v_pk_mul_f32 v[46:47], v[16:17], v[144:145] op_sel_hi:[1,0]
	v_pk_mul_f32 v[50:51], v[16:17], v[40:41] op_sel_hi:[1,0]
	v_pk_fma_f32 v[46:47], v[18:19], v[144:145], v[46:47] op_sel:[0,1,0] op_sel_hi:[1,1,1]
	v_pk_fma_f32 v[50:51], v[18:19], v[40:41], v[50:51] op_sel:[0,1,0] op_sel_hi:[1,1,1]
	v_pk_fma_f32 v[46:47], v[20:21], v[146:147], v[46:47] op_sel_hi:[1,0,1]
	v_pk_fma_f32 v[50:51], v[20:21], v[42:43], v[50:51] op_sel_hi:[1,0,1]
	v_pk_fma_f32 v[46:47], v[22:23], v[146:147], v[46:47] op_sel:[0,1,0] op_sel_hi:[1,1,1]
	v_pk_fma_f32 v[50:51], v[22:23], v[42:43], v[50:51] op_sel:[0,1,0] op_sel_hi:[1,1,1]
	ds_read_b128 v[40:43], v2 offset:3584
	v_pk_mul_f32 v[168:169], v[164:165], v[156:157] op_sel_hi:[1,0]
	v_add_f32_dpp v48, v47, v46 quad_perm:[1,0,3,2] row_mask:0xf bank_mask:0xf bound_ctrl:1
	v_add_f32_dpp v52, v51, v50 quad_perm:[1,0,3,2] row_mask:0xf bank_mask:0xf bound_ctrl:1
	v_pk_mul_f32 v[170:171], v[164:165], v[156:157] op_sel:[0,1] op_sel_hi:[1,1]
	v_add_f32_dpp v48, v48, v48 quad_perm:[2,3,0,1] row_mask:0xf bank_mask:0xf bound_ctrl:1
	v_pk_mul_f32 v[172:173], v[164:165], v[158:159] op_sel_hi:[1,0]
	v_pk_mul_f32 v[174:175], v[164:165], v[158:159] op_sel:[0,1] op_sel_hi:[1,1]
	v_add_f32_dpp v48, v48, v48 row_ror:4 row_mask:0xf bank_mask:0xf bound_ctrl:1
	v_pk_fma_f32 v[168:169], v[16:17], v[148:149], v[168:169] op_sel_hi:[1,0,1]
	v_pk_fma_f32 v[170:171], v[18:19], v[148:149], v[170:171] op_sel:[0,1,0] op_sel_hi:[1,1,1]
	v_add_f32_dpp v48, v48, v48 row_ror:8 row_mask:0xf bank_mask:0xf bound_ctrl:1
	v_pk_fma_f32 v[172:173], v[20:21], v[150:151], v[172:173] op_sel_hi:[1,0,1]
	v_pk_fma_f32 v[174:175], v[22:23], v[150:151], v[174:175] op_sel:[0,1,0] op_sel_hi:[1,1,1]
	v_mov_b32_dpp v49, v48 quad_perm:[1,0,3,2] row_mask:0xf bank_mask:0xf bound_ctrl:1
	v_pk_fma_f32 v[16:17], v[48:49], v[152:153], v[168:169] op_sel_hi:[1,0,1] neg_lo:[0,1,0] neg_hi:[0,1,0]
	v_pk_fma_f32 v[18:19], v[48:49], v[152:153], v[170:171] op_sel:[0,1,0] op_sel_hi:[1,1,1] neg_lo:[0,1,0] neg_hi:[0,1,0]
	v_pk_fma_f32 v[20:21], v[48:49], v[154:155], v[172:173] op_sel_hi:[1,0,1] neg_lo:[0,1,0] neg_hi:[0,1,0]
	v_pk_fma_f32 v[22:23], v[48:49], v[154:155], v[174:175] op_sel:[0,1,0] op_sel_hi:[1,1,1] neg_lo:[0,1,0] neg_hi:[0,1,0]
	ds_read_b128 v[144:147], v2 offset:20224
	ds_read_b64 v[164:165], v3 offset:16128
	ds_read_b128 v[156:159], v2 offset:12032
	ds_read_b128 v[148:151], v2 offset:7936
	ds_read_b128 v[152:155], v2 offset:24320
	s_waitcnt lgkmcnt(5)
	v_pk_mul_f32 v[46:47], v[16:17], v[24:25] op_sel_hi:[1,0]
	v_pk_mul_f32 v[50:51], v[16:17], v[160:161] op_sel_hi:[1,0]
	v_pk_fma_f32 v[46:47], v[18:19], v[24:25], v[46:47] op_sel:[0,1,0] op_sel_hi:[1,1,1]
	v_pk_fma_f32 v[50:51], v[18:19], v[160:161], v[50:51] op_sel:[0,1,0] op_sel_hi:[1,1,1]
	v_pk_fma_f32 v[46:47], v[20:21], v[26:27], v[46:47] op_sel_hi:[1,0,1]
	v_pk_fma_f32 v[50:51], v[20:21], v[162:163], v[50:51] op_sel_hi:[1,0,1]
	v_pk_fma_f32 v[46:47], v[22:23], v[26:27], v[46:47] op_sel:[0,1,0] op_sel_hi:[1,1,1]
	v_pk_fma_f32 v[50:51], v[22:23], v[162:163], v[50:51] op_sel:[0,1,0] op_sel_hi:[1,1,1]
	ds_read_b128 v[160:163], v2 offset:3840
	v_pk_mul_f32 v[168:169], v[44:45], v[36:37] op_sel_hi:[1,0]
	v_add_f32_dpp v48, v47, v46 quad_perm:[1,0,3,2] row_mask:0xf bank_mask:0xf bound_ctrl:1
	v_add_f32_dpp v53, v51, v50 quad_perm:[1,0,3,2] row_mask:0xf bank_mask:0xf bound_ctrl:1
	v_pk_mul_f32 v[170:171], v[44:45], v[36:37] op_sel:[0,1] op_sel_hi:[1,1]
	v_add_f32_dpp v48, v48, v48 quad_perm:[2,3,0,1] row_mask:0xf bank_mask:0xf bound_ctrl:1
	ds_write2st64_b32 v0, v52, v53 offset0:240 offset1:244
	v_pk_mul_f32 v[172:173], v[44:45], v[38:39] op_sel_hi:[1,0]
	v_pk_mul_f32 v[174:175], v[44:45], v[38:39] op_sel:[0,1] op_sel_hi:[1,1]
	v_add_f32_dpp v48, v48, v48 row_ror:4 row_mask:0xf bank_mask:0xf bound_ctrl:1
	v_pk_fma_f32 v[168:169], v[16:17], v[28:29], v[168:169] op_sel_hi:[1,0,1]
	v_pk_fma_f32 v[170:171], v[18:19], v[28:29], v[170:171] op_sel:[0,1,0] op_sel_hi:[1,1,1]
	v_add_f32_dpp v48, v48, v48 row_ror:8 row_mask:0xf bank_mask:0xf bound_ctrl:1
	v_pk_fma_f32 v[172:173], v[20:21], v[30:31], v[172:173] op_sel_hi:[1,0,1]
	v_pk_fma_f32 v[174:175], v[22:23], v[30:31], v[174:175] op_sel:[0,1,0] op_sel_hi:[1,1,1]
	v_mov_b32_dpp v49, v48 quad_perm:[1,0,3,2] row_mask:0xf bank_mask:0xf bound_ctrl:1
	v_pk_fma_f32 v[16:17], v[48:49], v[32:33], v[168:169] op_sel_hi:[1,0,1] neg_lo:[0,1,0] neg_hi:[0,1,0]
	v_pk_fma_f32 v[18:19], v[48:49], v[32:33], v[170:171] op_sel:[0,1,0] op_sel_hi:[1,1,1] neg_lo:[0,1,0] neg_hi:[0,1,0]
	v_pk_fma_f32 v[20:21], v[48:49], v[34:35], v[172:173] op_sel_hi:[1,0,1] neg_lo:[0,1,0] neg_hi:[0,1,0]
	v_pk_fma_f32 v[22:23], v[48:49], v[34:35], v[174:175] op_sel:[0,1,0] op_sel_hi:[1,1,1] neg_lo:[0,1,0] neg_hi:[0,1,0]
	s_waitcnt lgkmcnt(1)
	v_pk_mul_f32 v[46:47], v[16:17], v[144:145] op_sel_hi:[1,0]
	v_pk_mul_f32 v[50:51], v[16:17], v[40:41] op_sel_hi:[1,0]
	v_pk_fma_f32 v[46:47], v[18:19], v[144:145], v[46:47] op_sel:[0,1,0] op_sel_hi:[1,1,1]
	v_pk_fma_f32 v[50:51], v[18:19], v[40:41], v[50:51] op_sel:[0,1,0] op_sel_hi:[1,1,1]
	v_pk_fma_f32 v[46:47], v[20:21], v[146:147], v[46:47] op_sel_hi:[1,0,1]
	v_pk_fma_f32 v[50:51], v[20:21], v[42:43], v[50:51] op_sel_hi:[1,0,1]
	v_pk_fma_f32 v[46:47], v[22:23], v[146:147], v[46:47] op_sel:[0,1,0] op_sel_hi:[1,1,1]
	v_pk_fma_f32 v[50:51], v[22:23], v[42:43], v[50:51] op_sel:[0,1,0] op_sel_hi:[1,1,1]
	v_pk_mul_f32 v[168:169], v[164:165], v[156:157] op_sel_hi:[1,0]
	v_add_f32_dpp v48, v47, v46 quad_perm:[1,0,3,2] row_mask:0xf bank_mask:0xf bound_ctrl:1
	v_add_f32_dpp v52, v51, v50 quad_perm:[1,0,3,2] row_mask:0xf bank_mask:0xf bound_ctrl:1
	v_pk_mul_f32 v[170:171], v[164:165], v[156:157] op_sel:[0,1] op_sel_hi:[1,1]
	v_add_f32_dpp v48, v48, v48 quad_perm:[2,3,0,1] row_mask:0xf bank_mask:0xf bound_ctrl:1
	v_pk_mul_f32 v[172:173], v[164:165], v[158:159] op_sel_hi:[1,0]
	v_pk_mul_f32 v[174:175], v[164:165], v[158:159] op_sel:[0,1] op_sel_hi:[1,1]
	v_add_f32_dpp v48, v48, v48 row_ror:4 row_mask:0xf bank_mask:0xf bound_ctrl:1
	v_pk_fma_f32 v[168:169], v[16:17], v[148:149], v[168:169] op_sel_hi:[1,0,1]
	v_pk_fma_f32 v[170:171], v[18:19], v[148:149], v[170:171] op_sel:[0,1,0] op_sel_hi:[1,1,1]
	v_add_f32_dpp v48, v48, v48 row_ror:8 row_mask:0xf bank_mask:0xf bound_ctrl:1
	v_pk_fma_f32 v[172:173], v[20:21], v[150:151], v[172:173] op_sel_hi:[1,0,1]
	v_pk_fma_f32 v[174:175], v[22:23], v[150:151], v[174:175] op_sel:[0,1,0] op_sel_hi:[1,1,1]
	v_mov_b32_dpp v49, v48 quad_perm:[1,0,3,2] row_mask:0xf bank_mask:0xf bound_ctrl:1
	v_pk_fma_f32 v[16:17], v[48:49], v[152:153], v[168:169] op_sel_hi:[1,0,1] neg_lo:[0,1,0] neg_hi:[0,1,0]
	v_pk_fma_f32 v[18:19], v[48:49], v[152:153], v[170:171] op_sel:[0,1,0] op_sel_hi:[1,1,1] neg_lo:[0,1,0] neg_hi:[0,1,0]
	v_pk_fma_f32 v[20:21], v[48:49], v[154:155], v[172:173] op_sel_hi:[1,0,1] neg_lo:[0,1,0] neg_hi:[0,1,0]
	v_pk_fma_f32 v[22:23], v[48:49], v[154:155], v[174:175] op_sel:[0,1,0] op_sel_hi:[1,1,1] neg_lo:[0,1,0] neg_hi:[0,1,0]
	v_pk_mul_f32 v[50:51], v[16:17], v[160:161] op_sel_hi:[1,0]
	v_pk_fma_f32 v[50:51], v[18:19], v[160:161], v[50:51] op_sel:[0,1,0] op_sel_hi:[1,1,1]
	v_pk_fma_f32 v[50:51], v[20:21], v[162:163], v[50:51] op_sel_hi:[1,0,1]
	v_pk_fma_f32 v[50:51], v[22:23], v[162:163], v[50:51] op_sel:[0,1,0] op_sel_hi:[1,1,1]
	s_nop 1
	v_add_f32_dpp v53, v51, v50 quad_perm:[1,0,3,2] row_mask:0xf bank_mask:0xf bound_ctrl:1
	ds_write2st64_b32 v0, v52, v53 offset0:248 offset1:252
